# m14 + DSA top-k select count block: alternate vcc / s[6:7] carry operands, no VCC-hazard nops
# speedup vs baseline: 1.0040x; 1.0040x over previous
; template <class MP> DEVI void select_row(const float* sc, int c  , MP mrow, int lane) {
;     ...
;         int cl = 0;
; #pragma unroll
;         for (int j = 0; j < 32; ++j) cl += (u[j] >= cand) ? 1 : 0;
;         int cnt = 0;
; #pragma unroll
;         for (int b = 0; b < 6; ++b) cnt += __popcll(__ballot(((cl >> b) & 1) != 0)) << b;
;         if (cnt >= 256) { lo = cand; clo = cnt; if (cnt == 256) { exact = true; break; } rep = last == 0 ? rep + 1 : 1; last = 0; }
;         else { hi = cand; chi = cnt; rep = last == 1 ? rep + 1 : 1; last = 1; }
.LBB11_1388:
	s_mov_b64 s[6:7], 0
	s_and_b64 vcc, exec, s[8:9]
	s_cbranch_vccz .LBB11_1368
	v_mov_b32_e32 v66, 0
	s_mov_b64 s[8:9], -1
	v_cmp_le_u32_e32 vcc, s52, v1
	v_cmp_le_u32_e64 s[6:7], s52, v43
	s_nop 0
	v_addc_co_u32_e32 v66, vcc, 0, v66, vcc
	v_cmp_le_u32_e32 vcc, s52, v62
	v_addc_co_u32_e64 v66, s[6:7], 0, v66, s[6:7]
	v_cmp_le_u32_e64 s[6:7], s52, v9
	v_addc_co_u32_e32 v66, vcc, 0, v66, vcc
	v_cmp_le_u32_e32 vcc, s52, v64
	v_addc_co_u32_e64 v66, s[6:7], 0, v66, s[6:7]
	v_cmp_le_u32_e64 s[6:7], s52, v71
	v_addc_co_u32_e32 v66, vcc, 0, v66, vcc
	v_cmp_le_u32_e32 vcc, s52, v63
	v_addc_co_u32_e64 v66, s[6:7], 0, v66, s[6:7]
	v_cmp_le_u32_e64 s[6:7], s52, v61
	v_addc_co_u32_e32 v66, vcc, 0, v66, vcc
	v_cmp_le_u32_e32 vcc, s52, v59
	v_addc_co_u32_e64 v66, s[6:7], 0, v66, s[6:7]
	v_cmp_le_u32_e64 s[6:7], s52, v57
	v_addc_co_u32_e32 v66, vcc, 0, v66, vcc
	v_cmp_le_u32_e32 vcc, s52, v55
	v_addc_co_u32_e64 v66, s[6:7], 0, v66, s[6:7]
	v_cmp_le_u32_e64 s[6:7], s52, v53
	v_addc_co_u32_e32 v66, vcc, 0, v66, vcc
	v_cmp_le_u32_e32 vcc, s52, v51
	v_addc_co_u32_e64 v66, s[6:7], 0, v66, s[6:7]
	v_cmp_le_u32_e64 s[6:7], s52, v49
	v_addc_co_u32_e32 v66, vcc, 0, v66, vcc
	v_cmp_le_u32_e32 vcc, s52, v47
	v_addc_co_u32_e64 v66, s[6:7], 0, v66, s[6:7]
	v_cmp_le_u32_e64 s[6:7], s52, v45
	v_addc_co_u32_e32 v66, vcc, 0, v66, vcc
	v_cmp_le_u32_e32 vcc, s52, v41
	v_addc_co_u32_e64 v66, s[6:7], 0, v66, s[6:7]
	v_cmp_le_u32_e64 s[6:7], s52, v39
	v_addc_co_u32_e32 v66, vcc, 0, v66, vcc
	v_cmp_le_u32_e32 vcc, s52, v37
	v_addc_co_u32_e64 v66, s[6:7], 0, v66, s[6:7]
	v_cmp_le_u32_e64 s[6:7], s52, v35
	v_addc_co_u32_e32 v66, vcc, 0, v66, vcc
	v_cmp_le_u32_e32 vcc, s52, v33
	v_addc_co_u32_e64 v66, s[6:7], 0, v66, s[6:7]
	v_cmp_le_u32_e64 s[6:7], s52, v31
	v_addc_co_u32_e32 v66, vcc, 0, v66, vcc
	v_cmp_le_u32_e32 vcc, s52, v29
	v_addc_co_u32_e64 v66, s[6:7], 0, v66, s[6:7]
	v_cmp_le_u32_e64 s[6:7], s52, v27
	v_addc_co_u32_e32 v66, vcc, 0, v66, vcc
	v_cmp_le_u32_e32 vcc, s52, v25
	v_addc_co_u32_e64 v66, s[6:7], 0, v66, s[6:7]
	v_cmp_le_u32_e64 s[6:7], s52, v23
	v_addc_co_u32_e32 v66, vcc, 0, v66, vcc
	v_cmp_le_u32_e32 vcc, s52, v21
	v_addc_co_u32_e64 v66, s[6:7], 0, v66, s[6:7]
	v_cmp_le_u32_e64 s[6:7], s52, v19
	v_addc_co_u32_e32 v66, vcc, 0, v66, vcc
	v_cmp_le_u32_e32 vcc, s52, v17
	v_addc_co_u32_e64 v66, s[6:7], 0, v66, s[6:7]
	v_cmp_le_u32_e64 s[6:7], s52, v15
	v_addc_co_u32_e32 v66, vcc, 0, v66, vcc
	v_cmp_le_u32_e32 vcc, s52, v13
	v_addc_co_u32_e64 v66, s[6:7], 0, v66, s[6:7]
	v_cmp_le_u32_e64 s[6:7], s52, v11
	v_addc_co_u32_e32 v66, vcc, 0, v66, vcc
	s_nop 0
	v_addc_co_u32_e64 v66, s[6:7], 0, v66, s[6:7]
	v_and_b32_e32 v67, 1, v66
	v_cmp_ne_u32_e32 vcc, 0, v67
	v_bfe_u32 v67, v66, 1, 1
	s_bcnt1_i32_b64 s6, vcc
	v_cmp_ne_u32_e32 vcc, 0, v67
	s_bcnt1_i32_b64 s7, vcc
	v_bfe_u32 v67, v66, 2, 1
	s_lshl_b32 s7, s7, 1
	v_cmp_ne_u32_e32 vcc, 0, v67
	s_add_i32 s6, s7, s6
	s_bcnt1_i32_b64 s7, vcc
	v_bfe_u32 v67, v66, 3, 1
	s_lshl_b32 s7, s7, 2
	v_cmp_ne_u32_e32 vcc, 0, v67
	s_add_i32 s6, s6, s7
	s_bcnt1_i32_b64 s7, vcc
	v_bfe_u32 v67, v66, 4, 1
	s_lshl_b32 s7, s7, 3
	v_cmp_ne_u32_e32 vcc, 0, v67
	s_add_i32 s6, s6, s7
	s_bcnt1_i32_b64 s7, vcc
	v_bfe_u32 v66, v66, 5, 1
	s_lshl_b32 s7, s7, 4
	v_cmp_ne_u32_e32 vcc, 0, v66
	s_add_i32 s21, s6, s7
	s_bcnt1_i32_b64 s6, vcc
	s_lshl_b32 s6, s6, 5
	s_add_i32 s21, s21, s6
	s_mov_b64 s[6:7], -1
	s_cmpk_lt_u32 s21, 0x100
	s_cbranch_scc0 .LBB11_1391
	s_add_i32 s8, s20, 1
	s_cmp_eq_u32 s50, 1
	s_cselect_b32 s51, s8, 1
	s_mov_b64 s[8:9], 0
